# up-proj epilogue head loads batched; build_cum prefix sums batched (8 paired LDS reads per wait instead of 1)
# speedup vs baseline: 1.0410x; 1.0082x over previous
; __device__ __forceinline__ float ss_rstd(const u64_t* ss, int row) { return __builtin_amdgcn_rsqf((float)ss[row] * (SS_IFX / (float)2048) + 1e-6f); }
;     __device__ __forceinline__ void operator()(f32x4 (&acc)[2][2][4][2], const Unit& u, int wr, int wc, int fr_in, int fq_in) const {
;     ...
;         if (wv < 4) { const int cl = wv * 64 + fq * 16 + fr, ch = ((cl >> 7) ? DFF : 0) + u.pn * 128 + (cl & 127);
;             WL[cl] = cw[ch]; WL[256 + cl] = cw[UPW + ch]; WL[512 + cl] = cw[2 * UPW + ch]; WL[768 + cl] = cb[ch]; }
; #pragma unroll
;         for (int ai = 0; ai < 2; ++ai)
; #pragma unroll
;             for (int m = 0; m < 4; ++m) { asm volatile("" : "+v"(fr)); const float sc = ss_rstd(ss, u.pm * BM + ai * HALF + wr * 64 + m * 16 + fr);
; #pragma unroll
;                 for (int bj = 0; bj < 2; ++bj)
; #pragma unroll
;                     for (int n = 0; n < 2; ++n) acc[ai][bj][m][n] *= sc; }
.LBB0_59:
	v_mov_b32_e32 v171, v167
	v_mov_b32_e32 v170, v166
	v_readlane_b32 s40, v255, 10
	v_readlane_b32 s41, v255, 11
	v_lshlrev_b32_e32 v140, 4, v171
	v_readlane_b32 s1, v255, 9
	s_andn2_b64 vcc, exec, s[40:41]
	s_nop 0
	v_add3_u32 v140, v170, s1, v140
	s_cbranch_vccnz .LBB0_61
	s_movk_i32 s1, 0x80
	v_cmp_gt_u32_e32 vcc, s1, v140
	v_mov_b32_e32 v141, 0x1600
	s_movk_i32 s1, 0x7f
	v_cndmask_b32_e64 v141, v141, 0, vcc
	v_lshl_add_u32 v141, s81, 7, v141
	v_and_or_b32 v142, v140, s1, v141
	v_ashrrev_i32_e32 v143, 31, v142
	v_readlane_b32 s40, v254, 53
	v_lshlrev_b64 v[142:143], 2, v[142:143]
	v_readlane_b32 s41, v254, 54
	v_lshl_add_u32 v146, v140, 2, 0
	v_add_u32_e32 v148, 0x24d00, v146
	v_lshl_add_u64 v[144:145], s[40:41], 0, v[142:143]
	flat_load_dword v141, v[144:145]
	v_add_co_u32_e32 v146, vcc, 0xb000, v144
	v_readlane_b32 s40, v255, 5
	s_nop 0
	v_addc_co_u32_e32 v147, vcc, 0, v145, vcc
	v_add_co_u32_e32 v144, vcc, 0x16000, v144
	v_readlane_b32 s41, v255, 6
	s_nop 0
	v_addc_co_u32_e32 v145, vcc, 0, v145, vcc
	v_lshl_add_u64 v[142:143], s[40:41], 0, v[142:143]
	flat_load_dword v222, v[146:147]
	flat_load_dword v223, v[144:145]
	flat_load_dword v224, v[142:143]
	s_waitcnt vmcnt(0) lgkmcnt(0)
	ds_write_b32 v148, v141
	ds_write_b32 v148, v222 offset:1024
	ds_write_b32 v148, v223 offset:2048
	ds_write_b32 v148, v224 offset:3072
.LBB0_61:
	v_readlane_b32 s1, v253, 16
	s_lshl_b32 s29, s0, 8
	s_mul_i32 s0, s0, 44
	v_lshl_add_u32 v172, v140, 4, s1
	v_readlane_b32 s1, v255, 4
	s_add_i32 s29, s29, s1
	v_add_u32_e32 v140, s29, v170
	v_ashrrev_i32_e32 v141, 31, v140
	v_lshl_add_u64 v[140:141], v[140:141], 3, s[14:15]
	flat_load_dwordx2 v[192:193], v[140:141] offset:128
	flat_load_dwordx2 v[194:195], v[140:141] offset:256
	flat_load_dwordx2 v[196:197], v[140:141] offset:384
	flat_load_dwordx2 v[198:199], v[140:141] offset:1024
	flat_load_dwordx2 v[200:201], v[140:141] offset:1152
	flat_load_dwordx2 v[202:203], v[140:141] offset:1280
	flat_load_dwordx2 v[204:205], v[140:141] offset:1408
	flat_load_dwordx2 v[140:141], v[140:141]
	s_add_i32 s11, s29, 0x80
	s_add_i32 s1, s29, 0x90
	s_add_i32 s0, s0, s81
	v_readlane_b32 s48, v255, 12
	s_waitcnt vmcnt(0) lgkmcnt(0)
	v_ffbh_u32_e32 v142, v141
	v_min_u32_e32 v142, 32, v142
	v_lshlrev_b64 v[140:141], v142, v[140:141]
	v_min_u32_e32 v140, 1, v140
	v_or_b32_e32 v140, v141, v140
	v_cvt_f32_u32_e32 v140, v140
	v_sub_u32_e32 v141, 32, v142
	v_ldexp_f32 v140, v140, v141
	v_fmamk_f32 v140, v140, 0x2e000000, v207
	v_rsq_f32_e32 v140, v140
	s_nop 0
	v_pk_mul_f32 v[124:125], v[124:125], v[140:141] op_sel_hi:[1,0]
	v_pk_mul_f32 v[122:123], v[122:123], v[140:141] op_sel_hi:[1,0]
	v_pk_mul_f32 v[116:117], v[116:117], v[140:141] op_sel_hi:[1,0]
	v_pk_mul_f32 v[114:115], v[114:115], v[140:141] op_sel_hi:[1,0]
	v_pk_mul_f32 v[108:109], v[108:109], v[140:141] op_sel_hi:[1,0]
	v_pk_mul_f32 v[106:107], v[106:107], v[140:141] op_sel_hi:[1,0]
	v_pk_mul_f32 v[88:89], v[88:89], v[140:141] op_sel_hi:[1,0]
	v_pk_mul_f32 v[86:87], v[86:87], v[140:141] op_sel_hi:[1,0]
	v_add3_u32 v140, v170, s29, 16
	v_ashrrev_i32_e32 v141, 31, v140
	v_lshl_add_u64 v[140:141], v[140:141], 3, s[14:15]
	v_mov_b32_e32 v142, v192
	v_mov_b32_e32 v143, v193
	s_nop 0
	v_add3_u32 v140, v170, s29, 32
	v_ashrrev_i32_e32 v141, 31, v140
	v_lshl_add_u64 v[140:141], v[140:141], 3, s[14:15]
	v_mov_b32_e32 v140, v194
	v_mov_b32_e32 v141, v195
	s_nop 0
	v_add3_u32 v144, v170, s29, 48
	v_ashrrev_i32_e32 v145, 31, v144
	v_lshl_add_u64 v[144:145], v[144:145], 3, s[14:15]
	v_mov_b32_e32 v144, v196
	v_mov_b32_e32 v145, v197
	s_waitcnt vmcnt(0) lgkmcnt(0)
	v_ffbh_u32_e32 v146, v145
	v_min_u32_e32 v146, 32, v146
	v_lshlrev_b64 v[144:145], v146, v[144:145]
	v_min_u32_e32 v144, 1, v144
	v_or_b32_e32 v144, v145, v144
	v_cvt_f32_u32_e32 v144, v144
	v_sub_u32_e32 v145, 32, v146
	v_ldexp_f32 v144, v144, v145
	v_fmamk_f32 v144, v144, 0x2e000000, v207
	v_rsq_f32_e32 v144, v144
	s_nop 0
	v_pk_mul_f32 v[128:129], v[128:129], v[144:145] op_sel_hi:[1,0]
	v_pk_mul_f32 v[126:127], v[126:127], v[144:145] op_sel_hi:[1,0]
	v_pk_mul_f32 v[120:121], v[120:121], v[144:145] op_sel_hi:[1,0]
	v_pk_mul_f32 v[118:119], v[118:119], v[144:145] op_sel_hi:[1,0]
	v_pk_mul_f32 v[112:113], v[112:113], v[144:145] op_sel_hi:[1,0]
	v_pk_mul_f32 v[110:111], v[110:111], v[144:145] op_sel_hi:[1,0]
	v_pk_mul_f32 v[92:93], v[92:93], v[144:145] op_sel_hi:[1,0]
	v_pk_mul_f32 v[90:91], v[90:91], v[144:145] op_sel_hi:[1,0]
	v_add_u32_e32 v144, s11, v170
	v_ashrrev_i32_e32 v145, 31, v144
	v_lshl_add_u64 v[144:145], v[144:145], 3, s[14:15]
	v_mov_b32_e32 v144, v198
	v_mov_b32_e32 v145, v199
	s_waitcnt vmcnt(0) lgkmcnt(0)
; #define LAS __attribute__((address_space(3)))
; __device__ __forceinline__ float ss_rstd(const u64_t* ss, int row) { return __builtin_amdgcn_rsqf((float)ss[row] * (SS_IFX / (float)2048) + 1e-6f); }
;     __device__ __forceinline__ void operator()(f32x4 (&acc)[2][2][4][2], const Unit& u, int wr, int wc, int fr_in, int fq_in) const {
;     ...
; #pragma unroll
;         for (int ai = 0; ai < 2; ++ai)
; #pragma unroll
;             for (int m = 0; m < 4; ++m) { asm volatile("" : "+v"(fr)); const float sc = ss_rstd(ss, u.pm * BM + ai * HALF + wr * 64 + m * 16 + fr);
; #pragma unroll
;                 for (int bj = 0; bj < 2; ++bj)
; #pragma unroll
;                     for (int n = 0; n < 2; ++n) acc[ai][bj][m][n] *= sc; }
;         float* hb = HB + (size_t)(u.pm * (UPW / 256) + u.pn) * 1024;
; #pragma unroll
;         for (int ai = 0; ai < 2; ++ai) { const int blk = 2 * ai + wr;
;             asm volatile("" : "+v"(fr), "+v"(fq)); const int lc0 = wc * 32 + 8 * fq;
; #pragma unroll
;             for (int bj = 0; bj < 2; ++bj)
; #pragma unroll
;                 for (int n = 0; n < 2; ++n) {
;                     LAS float* d0 = fr == 0 ? HL + (blk * 2 + 0) * 256 + bj * 128 + lc0 + 4 * n : DMP;
;                     LAS float* d1 = fr == 15 ? HL + (blk * 2 + 1) * 256 + bj * 128 + lc0 + 4 * n : DMP;
;                     *(LAS f32x4*)d0 = acc[ai][bj][0][n]; *(LAS f32x4*)d1 = acc[ai][bj][3][n]; }
;         }
;         asm volatile("s_waitcnt lgkmcnt(0)" ::: "memory"); __builtin_amdgcn_s_barrier(); asm volatile("" ::: "memory");
;         if (wv == 0) { const int l4 = (fq * 16 + fr) * 4;
;             *(f32x4*)(hb + l4) = *(const LAS f32x4*)(HL + l4); *(f32x4*)(hb + 256 + l4) = *(const LAS f32x4*)(HL + 7 * 256 + l4); }
	v_ffbh_u32_e32 v146, v145
	v_min_u32_e32 v146, 32, v146
	v_lshlrev_b64 v[144:145], v146, v[144:145]
	v_min_u32_e32 v144, 1, v144
	v_or_b32_e32 v144, v145, v144
	v_cvt_f32_u32_e32 v144, v144
	v_sub_u32_e32 v145, 32, v146
	v_ldexp_f32 v144, v144, v145
	v_fmamk_f32 v144, v144, 0x2e000000, v207
	v_rsq_f32_e32 v144, v144
	s_nop 0
	v_pk_mul_f32 v[28:29], v[28:29], v[144:145] op_sel_hi:[1,0]
	v_pk_mul_f32 v[26:27], v[26:27], v[144:145] op_sel_hi:[1,0]
	v_pk_mul_f32 v[20:21], v[20:21], v[144:145] op_sel_hi:[1,0]
	v_pk_mul_f32 v[18:19], v[18:19], v[144:145] op_sel_hi:[1,0]
	v_pk_mul_f32 v[12:13], v[12:13], v[144:145] op_sel_hi:[1,0]
	v_pk_mul_f32 v[10:11], v[10:11], v[144:145] op_sel_hi:[1,0]
	v_pk_mul_f32 v[4:5], v[4:5], v[144:145] op_sel_hi:[1,0]
	v_pk_mul_f32 v[2:3], v[2:3], v[144:145] op_sel_hi:[1,0]
	v_add_u32_e32 v144, s1, v170
	v_ashrrev_i32_e32 v145, 31, v144
	v_lshl_add_u64 v[144:145], v[144:145], 3, s[14:15]
	s_add_i32 s1, s29, 0xa0
	v_mov_b32_e32 v146, v200
	v_mov_b32_e32 v147, v201
	s_nop 0
	v_add_u32_e32 v144, s1, v170
	v_ashrrev_i32_e32 v145, 31, v144
	v_lshl_add_u64 v[144:145], v[144:145], 3, s[14:15]
	s_add_i32 s1, s29, 0xb0
	v_mov_b32_e32 v144, v202
	v_mov_b32_e32 v145, v203
	s_nop 0
	v_add_u32_e32 v148, s1, v170
	v_ashrrev_i32_e32 v149, 31, v148
	v_lshl_add_u64 v[148:149], v[148:149], 3, s[14:15]
	v_mov_b32_e32 v148, v204
	v_mov_b32_e32 v149, v205
	s_ashr_i32 s1, s0, 31
	s_lshl_b64 s[40:41], s[0:1], 12
	v_cmp_eq_u32_e64 s[0:1], 0, v170
	v_cmp_eq_u32_e32 vcc, 15, v170
	s_waitcnt vmcnt(0) lgkmcnt(0)
	v_ffbh_u32_e32 v150, v149
	v_min_u32_e32 v150, 32, v150
	v_lshlrev_b64 v[148:149], v150, v[148:149]
	v_min_u32_e32 v148, 1, v148
	v_or_b32_e32 v148, v149, v148
	v_cvt_f32_u32_e32 v148, v148
	v_sub_u32_e32 v149, 32, v150
	v_ldexp_f32 v148, v148, v149
	v_fmamk_f32 v148, v148, 0x2e000000, v207
	v_rsq_f32_e32 v148, v148
	s_nop 0
	v_pk_mul_f32 v[32:33], v[32:33], v[148:149] op_sel_hi:[1,0]
	v_pk_mul_f32 v[30:31], v[30:31], v[148:149] op_sel_hi:[1,0]
	v_pk_mul_f32 v[24:25], v[24:25], v[148:149] op_sel_hi:[1,0]
	v_pk_mul_f32 v[22:23], v[22:23], v[148:149] op_sel_hi:[1,0]
	v_pk_mul_f32 v[16:17], v[16:17], v[148:149] op_sel_hi:[1,0]
	v_pk_mul_f32 v[14:15], v[14:15], v[148:149] op_sel_hi:[1,0]
	v_pk_mul_f32 v[8:9], v[8:9], v[148:149] op_sel_hi:[1,0]
	v_pk_mul_f32 v[6:7], v[6:7], v[148:149] op_sel_hi:[1,0]
	v_lshl_add_u32 v148, v171, 3, s68
	v_lshl_add_u32 v148, v148, 2, s48
	v_cndmask_b32_e64 v149, v172, v148, s[0:1]
	v_add_u32_e32 v150, 0x400, v148
	v_cndmask_b32_e32 v150, v172, v150, vcc
	ds_write_b128 v149, v[122:125]
	ds_write_b128 v150, v[126:129]
	v_add_u32_e32 v149, 16, v148
	v_cndmask_b32_e64 v149, v172, v149, s[0:1]
	v_add_u32_e32 v150, 0x410, v148
	v_cndmask_b32_e32 v150, v172, v150, vcc
	ds_write_b128 v149, v[114:117]
	ds_write_b128 v150, v[118:121]
	v_add_u32_e32 v149, 0x200, v148
	v_cndmask_b32_e64 v149, v172, v149, s[0:1]
	v_add_u32_e32 v150, 0x600, v148
	v_cndmask_b32_e32 v150, v172, v150, vcc
	ds_write_b128 v149, v[106:109]
	ds_write_b128 v150, v[110:113]
	v_add_u32_e32 v149, 0x210, v148
	v_add_u32_e32 v148, 0x610, v148
	v_cndmask_b32_e64 v149, v172, v149, s[0:1]
	v_cndmask_b32_e32 v148, v172, v148, vcc
	ds_write_b128 v149, v[86:89]
	ds_write_b128 v148, v[90:93]
	v_readlane_b32 s48, v255, 13
	v_lshl_add_u32 v148, v171, 3, s68
	v_cmp_eq_u32_e32 vcc, 0, v170
	v_lshl_add_u32 v148, v148, 2, s48
	v_cmp_eq_u32_e64 s[0:1], 15, v170
	v_cndmask_b32_e32 v149, v172, v148, vcc
	v_add_u32_e32 v150, 0x400, v148
	v_cndmask_b32_e64 v150, v172, v150, s[0:1]
	ds_write_b128 v149, v[26:29]
	ds_write_b128 v150, v[30:33]
	v_add_u32_e32 v149, 16, v148
	v_cndmask_b32_e32 v149, v172, v149, vcc
	v_add_u32_e32 v150, 0x410, v148
	v_cndmask_b32_e64 v150, v172, v150, s[0:1]
	ds_write_b128 v149, v[18:21]
	ds_write_b128 v150, v[22:25]
	v_add_u32_e32 v149, 0x200, v148
	v_cndmask_b32_e32 v149, v172, v149, vcc
	v_add_u32_e32 v150, 0x600, v148
	v_cndmask_b32_e64 v150, v172, v150, s[0:1]
	ds_write_b128 v149, v[10:13]
	ds_write_b128 v150, v[14:17]
	v_add_u32_e32 v149, 0x210, v148
	v_cndmask_b32_e32 v149, v172, v149, vcc
	v_add_u32_e32 v148, 0x610, v148
	v_cndmask_b32_e64 v148, v172, v148, s[0:1]
	ds_write_b128 v149, v[2:5]
	ds_write_b128 v148, v[6:9]
	s_waitcnt lgkmcnt(0)
	s_barrier
	s_add_u32 s0, s6, s40
	v_cndmask_b32_e64 v148, 0, 1, s[4:5]
	s_addc_u32 s1, s7, s41
	v_cmp_ne_u32_e64 s[40:41], 1, v148
	s_andn2_b64 vcc, exec, s[4:5]
	s_cbranch_vccnz .LBB0_63
	v_lshlrev_b32_e32 v148, 6, v171
	v_lshl_add_u32 v152, v170, 2, v148
	v_lshl_add_u32 v154, v152, 2, 0
	v_add_u32_e32 v148, 0x20100, v154
	ds_read_b128 v[148:151], v148
	v_ashrrev_i32_e32 v153, 31, v152
	v_lshl_add_u64 v[152:153], v[152:153], 2, s[0:1]
	s_waitcnt lgkmcnt(0)
	flat_store_dwordx4 v[152:153], v[148:151]
	s_nop 1
	v_add_u32_e32 v148, 0x21d00, v154
	ds_read_b128 v[148:151], v148
	s_waitcnt lgkmcnt(0)
	flat_store_dwordx4 v[152:153], v[148:151] offset:1024

; __device__ __forceinline__ void build_cum(const Args& a, int L, int hl, long R0, const bf16_t* __restrict__ proj, LAS unsigned char* lds) {
;     ...
;     if (tid < 128) { const int d = tid >> 6; float run = 0.f;
;         if (d == 0) {
; #pragma unroll 8
;             for (int i = 0; i < 64; ++i) { run += cum[i * 64 + k]; cum[i * 64 + k] = run; }
;         } else {
; #pragma unroll 8
;             for (int i = 63; i >= 0; --i) { run += cum[(64 + i) * 64 + k]; cum[(64 + i) * 64 + k] = run; }
;         } }
.LBB0_127:
	ds_read2st64_b32 v[52:53], v0 offset0:126 offset1:127
	ds_read2st64_b32 v[54:55], v0 offset0:124 offset1:125
	ds_read2st64_b32 v[56:57], v0 offset0:122 offset1:123
	ds_read2st64_b32 v[58:59], v0 offset0:120 offset1:121
	ds_read2st64_b32 v[60:61], v0 offset0:118 offset1:119
	ds_read2st64_b32 v[62:63], v0 offset0:116 offset1:117
	ds_read2st64_b32 v[64:65], v0 offset0:114 offset1:115
	ds_read2st64_b32 v[66:67], v0 offset0:112 offset1:113
	s_waitcnt lgkmcnt(7)
	v_add_f32_e32 v53, v2, v53
	v_add_f32_e32 v52, v53, v52
	v_mov_b32_e32 v2, v52
	s_waitcnt lgkmcnt(6)
	v_add_f32_e32 v55, v2, v55
	v_add_f32_e32 v54, v55, v54
	v_mov_b32_e32 v2, v54
	s_waitcnt lgkmcnt(5)
	v_add_f32_e32 v57, v2, v57
	v_add_f32_e32 v56, v57, v56
	v_mov_b32_e32 v2, v56
	s_waitcnt lgkmcnt(4)
	v_add_f32_e32 v59, v2, v59
	v_add_f32_e32 v58, v59, v58
	v_mov_b32_e32 v2, v58
	s_waitcnt lgkmcnt(3)
	v_add_f32_e32 v61, v2, v61
	v_add_f32_e32 v60, v61, v60
	v_mov_b32_e32 v2, v60
	s_waitcnt lgkmcnt(2)
	v_add_f32_e32 v63, v2, v63
	v_add_f32_e32 v62, v63, v62
	v_mov_b32_e32 v2, v62
	s_waitcnt lgkmcnt(1)
	v_add_f32_e32 v65, v2, v65
	v_add_f32_e32 v64, v65, v64
	v_mov_b32_e32 v2, v64
	s_waitcnt lgkmcnt(0)
	v_add_f32_e32 v67, v2, v67
	v_add_f32_e32 v66, v67, v66
	v_mov_b32_e32 v2, v66
	ds_write2st64_b32 v0, v52, v53 offset0:126 offset1:127
	ds_write2st64_b32 v0, v54, v55 offset0:124 offset1:125
	ds_write2st64_b32 v0, v56, v57 offset0:122 offset1:123
	ds_write2st64_b32 v0, v58, v59 offset0:120 offset1:121
	ds_write2st64_b32 v0, v60, v61 offset0:118 offset1:119
	ds_write2st64_b32 v0, v62, v63 offset0:116 offset1:117
	ds_write2st64_b32 v0, v64, v65 offset0:114 offset1:115
	ds_write2st64_b32 v0, v66, v67 offset0:112 offset1:113
	s_waitcnt lgkmcnt(0)
	ds_read2st64_b32 v[52:53], v0 offset0:110 offset1:111
	ds_read2st64_b32 v[54:55], v0 offset0:108 offset1:109
	ds_read2st64_b32 v[56:57], v0 offset0:106 offset1:107
	ds_read2st64_b32 v[58:59], v0 offset0:104 offset1:105
	ds_read2st64_b32 v[60:61], v0 offset0:102 offset1:103
	ds_read2st64_b32 v[62:63], v0 offset0:100 offset1:101
	ds_read2st64_b32 v[64:65], v0 offset0:98 offset1:99
	ds_read2st64_b32 v[66:67], v0 offset0:96 offset1:97
	s_waitcnt lgkmcnt(7)
	v_add_f32_e32 v53, v2, v53
	v_add_f32_e32 v52, v53, v52
	v_mov_b32_e32 v2, v52
	s_waitcnt lgkmcnt(6)
	v_add_f32_e32 v55, v2, v55
	v_add_f32_e32 v54, v55, v54
	v_mov_b32_e32 v2, v54
	s_waitcnt lgkmcnt(5)
	v_add_f32_e32 v57, v2, v57
	v_add_f32_e32 v56, v57, v56
	v_mov_b32_e32 v2, v56
	s_waitcnt lgkmcnt(4)
	v_add_f32_e32 v59, v2, v59
	v_add_f32_e32 v58, v59, v58
	v_mov_b32_e32 v2, v58
	s_waitcnt lgkmcnt(3)
	v_add_f32_e32 v61, v2, v61
	v_add_f32_e32 v60, v61, v60
	v_mov_b32_e32 v2, v60
	s_waitcnt lgkmcnt(2)
	v_add_f32_e32 v63, v2, v63
	v_add_f32_e32 v62, v63, v62
	v_mov_b32_e32 v2, v62
	s_waitcnt lgkmcnt(1)
	v_add_f32_e32 v65, v2, v65
	v_add_f32_e32 v64, v65, v64
	v_mov_b32_e32 v2, v64
	s_waitcnt lgkmcnt(0)
	v_add_f32_e32 v67, v2, v67
	v_add_f32_e32 v66, v67, v66
	v_mov_b32_e32 v2, v66
	ds_write2st64_b32 v0, v52, v53 offset0:110 offset1:111
	ds_write2st64_b32 v0, v54, v55 offset0:108 offset1:109
	ds_write2st64_b32 v0, v56, v57 offset0:106 offset1:107
	ds_write2st64_b32 v0, v58, v59 offset0:104 offset1:105
	ds_write2st64_b32 v0, v60, v61 offset0:102 offset1:103
	ds_write2st64_b32 v0, v62, v63 offset0:100 offset1:101
	ds_write2st64_b32 v0, v64, v65 offset0:98 offset1:99
	ds_write2st64_b32 v0, v66, v67 offset0:96 offset1:97
	s_waitcnt lgkmcnt(0)
	ds_read2st64_b32 v[52:53], v0 offset0:94 offset1:95
	ds_read2st64_b32 v[54:55], v0 offset0:92 offset1:93
	ds_read2st64_b32 v[56:57], v0 offset0:90 offset1:91
	ds_read2st64_b32 v[58:59], v0 offset0:88 offset1:89
	ds_read2st64_b32 v[60:61], v0 offset0:86 offset1:87
	ds_read2st64_b32 v[62:63], v0 offset0:84 offset1:85
	ds_read2st64_b32 v[64:65], v0 offset0:82 offset1:83
	ds_read2st64_b32 v[66:67], v0 offset0:80 offset1:81
	s_waitcnt lgkmcnt(7)
	v_add_f32_e32 v53, v2, v53
	v_add_f32_e32 v52, v53, v52
	v_mov_b32_e32 v2, v52
	s_waitcnt lgkmcnt(6)
	v_add_f32_e32 v55, v2, v55
	v_add_f32_e32 v54, v55, v54
	v_mov_b32_e32 v2, v54
	s_waitcnt lgkmcnt(5)
	v_add_f32_e32 v57, v2, v57
	v_add_f32_e32 v56, v57, v56
	v_mov_b32_e32 v2, v56
	s_waitcnt lgkmcnt(4)
	v_add_f32_e32 v59, v2, v59
	v_add_f32_e32 v58, v59, v58
	v_mov_b32_e32 v2, v58
	s_waitcnt lgkmcnt(3)
	v_add_f32_e32 v61, v2, v61
	v_add_f32_e32 v60, v61, v60
	v_mov_b32_e32 v2, v60
	s_waitcnt lgkmcnt(2)
	v_add_f32_e32 v63, v2, v63
	v_add_f32_e32 v62, v63, v62
	v_mov_b32_e32 v2, v62
	s_waitcnt lgkmcnt(1)
	v_add_f32_e32 v65, v2, v65
	v_add_f32_e32 v64, v65, v64
	v_mov_b32_e32 v2, v64
	s_waitcnt lgkmcnt(0)
	v_add_f32_e32 v67, v2, v67
	v_add_f32_e32 v66, v67, v66
	v_mov_b32_e32 v2, v66
	ds_write2st64_b32 v0, v52, v53 offset0:94 offset1:95
	ds_write2st64_b32 v0, v54, v55 offset0:92 offset1:93
	ds_write2st64_b32 v0, v56, v57 offset0:90 offset1:91
	ds_write2st64_b32 v0, v58, v59 offset0:88 offset1:89
	ds_write2st64_b32 v0, v60, v61 offset0:86 offset1:87
	ds_write2st64_b32 v0, v62, v63 offset0:84 offset1:85
	ds_write2st64_b32 v0, v64, v65 offset0:82 offset1:83
	ds_write2st64_b32 v0, v66, v67 offset0:80 offset1:81
	s_waitcnt lgkmcnt(0)
	ds_read2st64_b32 v[52:53], v0 offset0:78 offset1:79
	ds_read2st64_b32 v[54:55], v0 offset0:76 offset1:77
	ds_read2st64_b32 v[56:57], v0 offset0:74 offset1:75
	ds_read2st64_b32 v[58:59], v0 offset0:72 offset1:73
	ds_read2st64_b32 v[60:61], v0 offset0:70 offset1:71
	ds_read2st64_b32 v[62:63], v0 offset0:68 offset1:69
	ds_read2st64_b32 v[64:65], v0 offset0:66 offset1:67
	ds_read2st64_b32 v[66:67], v0 offset0:64 offset1:65
	s_waitcnt lgkmcnt(7)
	v_add_f32_e32 v53, v2, v53
	v_add_f32_e32 v52, v53, v52
	v_mov_b32_e32 v2, v52
	s_waitcnt lgkmcnt(6)
	v_add_f32_e32 v55, v2, v55
	v_add_f32_e32 v54, v55, v54
	v_mov_b32_e32 v2, v54
	s_waitcnt lgkmcnt(5)
	v_add_f32_e32 v57, v2, v57
	v_add_f32_e32 v56, v57, v56
	v_mov_b32_e32 v2, v56
	s_waitcnt lgkmcnt(4)
	v_add_f32_e32 v59, v2, v59
	v_add_f32_e32 v58, v59, v58
	v_mov_b32_e32 v2, v58
	s_waitcnt lgkmcnt(3)
	v_add_f32_e32 v61, v2, v61
	v_add_f32_e32 v60, v61, v60
	v_mov_b32_e32 v2, v60
	s_waitcnt lgkmcnt(2)
	v_add_f32_e32 v63, v2, v63
	v_add_f32_e32 v62, v63, v62
	v_mov_b32_e32 v2, v62
	s_waitcnt lgkmcnt(1)
	v_add_f32_e32 v65, v2, v65
	v_add_f32_e32 v64, v65, v64
	v_mov_b32_e32 v2, v64
	s_waitcnt lgkmcnt(0)
	v_add_f32_e32 v67, v2, v67
	v_add_f32_e32 v66, v67, v66
	v_mov_b32_e32 v2, v66
	ds_write2st64_b32 v0, v52, v53 offset0:78 offset1:79
	ds_write2st64_b32 v0, v54, v55 offset0:76 offset1:77
	ds_write2st64_b32 v0, v56, v57 offset0:74 offset1:75
	ds_write2st64_b32 v0, v58, v59 offset0:72 offset1:73
	ds_write2st64_b32 v0, v60, v61 offset0:70 offset1:71
	ds_write2st64_b32 v0, v62, v63 offset0:68 offset1:69
	ds_write2st64_b32 v0, v64, v65 offset0:66 offset1:67
	ds_write2st64_b32 v0, v66, v67 offset0:64 offset1:65
	s_waitcnt lgkmcnt(0)

; __device__ __forceinline__ void build_cum(const Args& a, int L, int hl, long R0, const bf16_t* __restrict__ proj, LAS unsigned char* lds) {
;     ...
;     if (tid < 128) { const int d = tid >> 6; float run = 0.f;
;         if (d == 0) {
; #pragma unroll 8
;             for (int i = 0; i < 64; ++i) { run += cum[i * 64 + k]; cum[i * 64 + k] = run; }
.LBB0_130:
	ds_read2st64_b32 v[52:53], v0 offset0:0 offset1:1
	ds_read2st64_b32 v[54:55], v0 offset0:2 offset1:3
	ds_read2st64_b32 v[56:57], v0 offset0:4 offset1:5
	ds_read2st64_b32 v[58:59], v0 offset0:6 offset1:7
	ds_read2st64_b32 v[60:61], v0 offset0:8 offset1:9
	ds_read2st64_b32 v[62:63], v0 offset0:10 offset1:11
	ds_read2st64_b32 v[64:65], v0 offset0:12 offset1:13
	ds_read2st64_b32 v[66:67], v0 offset0:14 offset1:15
	s_waitcnt lgkmcnt(7)
	v_add_f32_e32 v52, v2, v52
	v_add_f32_e32 v53, v52, v53
	v_mov_b32_e32 v2, v53
	s_waitcnt lgkmcnt(6)
	v_add_f32_e32 v54, v2, v54
	v_add_f32_e32 v55, v54, v55
	v_mov_b32_e32 v2, v55
	s_waitcnt lgkmcnt(5)
	v_add_f32_e32 v56, v2, v56
	v_add_f32_e32 v57, v56, v57
	v_mov_b32_e32 v2, v57
	s_waitcnt lgkmcnt(4)
	v_add_f32_e32 v58, v2, v58
	v_add_f32_e32 v59, v58, v59
	v_mov_b32_e32 v2, v59
	s_waitcnt lgkmcnt(3)
	v_add_f32_e32 v60, v2, v60
	v_add_f32_e32 v61, v60, v61
	v_mov_b32_e32 v2, v61
	s_waitcnt lgkmcnt(2)
	v_add_f32_e32 v62, v2, v62
	v_add_f32_e32 v63, v62, v63
	v_mov_b32_e32 v2, v63
	s_waitcnt lgkmcnt(1)
	v_add_f32_e32 v64, v2, v64
	v_add_f32_e32 v65, v64, v65
	v_mov_b32_e32 v2, v65
	s_waitcnt lgkmcnt(0)
	v_add_f32_e32 v66, v2, v66
	v_add_f32_e32 v67, v66, v67
	v_mov_b32_e32 v2, v67
	ds_write2st64_b32 v0, v52, v53 offset0:0 offset1:1
	ds_write2st64_b32 v0, v54, v55 offset0:2 offset1:3
	ds_write2st64_b32 v0, v56, v57 offset0:4 offset1:5
	ds_write2st64_b32 v0, v58, v59 offset0:6 offset1:7
	ds_write2st64_b32 v0, v60, v61 offset0:8 offset1:9
	ds_write2st64_b32 v0, v62, v63 offset0:10 offset1:11
	ds_write2st64_b32 v0, v64, v65 offset0:12 offset1:13
	ds_write2st64_b32 v0, v66, v67 offset0:14 offset1:15
	s_waitcnt lgkmcnt(0)
	ds_read2st64_b32 v[52:53], v0 offset0:16 offset1:17
	ds_read2st64_b32 v[54:55], v0 offset0:18 offset1:19
	ds_read2st64_b32 v[56:57], v0 offset0:20 offset1:21
	ds_read2st64_b32 v[58:59], v0 offset0:22 offset1:23
	ds_read2st64_b32 v[60:61], v0 offset0:24 offset1:25
	ds_read2st64_b32 v[62:63], v0 offset0:26 offset1:27
	ds_read2st64_b32 v[64:65], v0 offset0:28 offset1:29
	ds_read2st64_b32 v[66:67], v0 offset0:30 offset1:31
	s_waitcnt lgkmcnt(7)
	v_add_f32_e32 v52, v2, v52
	v_add_f32_e32 v53, v52, v53
	v_mov_b32_e32 v2, v53
	s_waitcnt lgkmcnt(6)
	v_add_f32_e32 v54, v2, v54
	v_add_f32_e32 v55, v54, v55
	v_mov_b32_e32 v2, v55
	s_waitcnt lgkmcnt(5)
	v_add_f32_e32 v56, v2, v56
	v_add_f32_e32 v57, v56, v57
	v_mov_b32_e32 v2, v57
	s_waitcnt lgkmcnt(4)
	v_add_f32_e32 v58, v2, v58
	v_add_f32_e32 v59, v58, v59
	v_mov_b32_e32 v2, v59
	s_waitcnt lgkmcnt(3)
	v_add_f32_e32 v60, v2, v60
	v_add_f32_e32 v61, v60, v61
	v_mov_b32_e32 v2, v61
	s_waitcnt lgkmcnt(2)
	v_add_f32_e32 v62, v2, v62
	v_add_f32_e32 v63, v62, v63
	v_mov_b32_e32 v2, v63
	s_waitcnt lgkmcnt(1)
	v_add_f32_e32 v64, v2, v64
	v_add_f32_e32 v65, v64, v65
	v_mov_b32_e32 v2, v65
	s_waitcnt lgkmcnt(0)
	v_add_f32_e32 v66, v2, v66
	v_add_f32_e32 v67, v66, v67
	v_mov_b32_e32 v2, v67
	ds_write2st64_b32 v0, v52, v53 offset0:16 offset1:17
	ds_write2st64_b32 v0, v54, v55 offset0:18 offset1:19
	ds_write2st64_b32 v0, v56, v57 offset0:20 offset1:21
	ds_write2st64_b32 v0, v58, v59 offset0:22 offset1:23
	ds_write2st64_b32 v0, v60, v61 offset0:24 offset1:25
	ds_write2st64_b32 v0, v62, v63 offset0:26 offset1:27
	ds_write2st64_b32 v0, v64, v65 offset0:28 offset1:29
	ds_write2st64_b32 v0, v66, v67 offset0:30 offset1:31
	s_waitcnt lgkmcnt(0)
	ds_read2st64_b32 v[52:53], v0 offset0:32 offset1:33
	ds_read2st64_b32 v[54:55], v0 offset0:34 offset1:35
	ds_read2st64_b32 v[56:57], v0 offset0:36 offset1:37
	ds_read2st64_b32 v[58:59], v0 offset0:38 offset1:39
	ds_read2st64_b32 v[60:61], v0 offset0:40 offset1:41
	ds_read2st64_b32 v[62:63], v0 offset0:42 offset1:43
	ds_read2st64_b32 v[64:65], v0 offset0:44 offset1:45
	ds_read2st64_b32 v[66:67], v0 offset0:46 offset1:47
	s_waitcnt lgkmcnt(7)
	v_add_f32_e32 v52, v2, v52
	v_add_f32_e32 v53, v52, v53
	v_mov_b32_e32 v2, v53
	s_waitcnt lgkmcnt(6)
	v_add_f32_e32 v54, v2, v54
	v_add_f32_e32 v55, v54, v55
	v_mov_b32_e32 v2, v55
	s_waitcnt lgkmcnt(5)
	v_add_f32_e32 v56, v2, v56
	v_add_f32_e32 v57, v56, v57
	v_mov_b32_e32 v2, v57
	s_waitcnt lgkmcnt(4)
	v_add_f32_e32 v58, v2, v58
	v_add_f32_e32 v59, v58, v59
	v_mov_b32_e32 v2, v59
	s_waitcnt lgkmcnt(3)
	v_add_f32_e32 v60, v2, v60
	v_add_f32_e32 v61, v60, v61
	v_mov_b32_e32 v2, v61
	s_waitcnt lgkmcnt(2)
	v_add_f32_e32 v62, v2, v62
	v_add_f32_e32 v63, v62, v63
	v_mov_b32_e32 v2, v63
	s_waitcnt lgkmcnt(1)
	v_add_f32_e32 v64, v2, v64
	v_add_f32_e32 v65, v64, v65
	v_mov_b32_e32 v2, v65
	s_waitcnt lgkmcnt(0)
	v_add_f32_e32 v66, v2, v66
	v_add_f32_e32 v67, v66, v67
	v_mov_b32_e32 v2, v67
	ds_write2st64_b32 v0, v52, v53 offset0:32 offset1:33
	ds_write2st64_b32 v0, v54, v55 offset0:34 offset1:35
	ds_write2st64_b32 v0, v56, v57 offset0:36 offset1:37
	ds_write2st64_b32 v0, v58, v59 offset0:38 offset1:39
	ds_write2st64_b32 v0, v60, v61 offset0:40 offset1:41
	ds_write2st64_b32 v0, v62, v63 offset0:42 offset1:43
	ds_write2st64_b32 v0, v64, v65 offset0:44 offset1:45
	ds_write2st64_b32 v0, v66, v67 offset0:46 offset1:47
	s_waitcnt lgkmcnt(0)
	ds_read2st64_b32 v[52:53], v0 offset0:48 offset1:49
	ds_read2st64_b32 v[54:55], v0 offset0:50 offset1:51
	ds_read2st64_b32 v[56:57], v0 offset0:52 offset1:53
	ds_read2st64_b32 v[58:59], v0 offset0:54 offset1:55
	ds_read2st64_b32 v[60:61], v0 offset0:56 offset1:57
	ds_read2st64_b32 v[62:63], v0 offset0:58 offset1:59
	ds_read2st64_b32 v[64:65], v0 offset0:60 offset1:61
	ds_read2st64_b32 v[66:67], v0 offset0:62 offset1:63
	s_waitcnt lgkmcnt(7)
	v_add_f32_e32 v52, v2, v52
	v_add_f32_e32 v53, v52, v53
	v_mov_b32_e32 v2, v53
	s_waitcnt lgkmcnt(6)
	v_add_f32_e32 v54, v2, v54
	v_add_f32_e32 v55, v54, v55
	v_mov_b32_e32 v2, v55
	s_waitcnt lgkmcnt(5)
	v_add_f32_e32 v56, v2, v56
	v_add_f32_e32 v57, v56, v57
	v_mov_b32_e32 v2, v57
	s_waitcnt lgkmcnt(4)
	v_add_f32_e32 v58, v2, v58
	v_add_f32_e32 v59, v58, v59
	v_mov_b32_e32 v2, v59
	s_waitcnt lgkmcnt(3)
	v_add_f32_e32 v60, v2, v60
	v_add_f32_e32 v61, v60, v61
	v_mov_b32_e32 v2, v61
	s_waitcnt lgkmcnt(2)
	v_add_f32_e32 v62, v2, v62
	v_add_f32_e32 v63, v62, v63
	v_mov_b32_e32 v2, v63
	s_waitcnt lgkmcnt(1)
	v_add_f32_e32 v64, v2, v64
	v_add_f32_e32 v65, v64, v65
	v_mov_b32_e32 v2, v65
	s_waitcnt lgkmcnt(0)
	v_add_f32_e32 v66, v2, v66
	v_add_f32_e32 v67, v66, v67
	v_mov_b32_e32 v2, v67
	ds_write2st64_b32 v0, v52, v53 offset0:48 offset1:49
	ds_write2st64_b32 v0, v54, v55 offset0:50 offset1:51
	ds_write2st64_b32 v0, v56, v57 offset0:52 offset1:53
	ds_write2st64_b32 v0, v58, v59 offset0:54 offset1:55
	ds_write2st64_b32 v0, v60, v61 offset0:56 offset1:57
	ds_write2st64_b32 v0, v62, v63 offset0:58 offset1:59
	ds_write2st64_b32 v0, v64, v65 offset0:60 offset1:61
	ds_write2st64_b32 v0, v66, v67 offset0:62 offset1:63
	s_waitcnt lgkmcnt(0)
